# attention units: one static priority raise (s_setprio 1) for waves 4-7 during the unit, reset before the combine
# speedup vs baseline: 1.0048x; 1.0048x over previous
; __device__ __forceinline__ float bf_lo(unsigned w) { return __uint_as_float(w << 16); }
; __device__ __forceinline__ float bf_hi(unsigned w) { return __uint_as_float(w & 0xffff0000u); }
; __device__ __forceinline__ unsigned pk2(float lo, float hi) { return pg8::cvt_pk_bf16(lo, hi); }
; __global__ void __launch_bounds__(NWAVES * 64, 2) trunk_fwd(Args args) {
;     ...
;                     { int lane_ = threadIdx.x & 63; asm volatile("" : "+v"(lane_));
;                       const float lam = LAM[li], post = 1.0f - (li == 0 ? LAMBDA_INIT0 : LAMBDA_INIT2);
;                       const f32x4* gp = (const f32x4*)(ARGIN(I_SUBLN) + li * 128 + (lane_ & 15) * 8); const f32x4 ga = gp[0], gb = gp[1];
;                       const size_t rowbase = (size_t)b * SEQ + (size_t)qb * 256 + wid * 32 + (lane_ >> 4); const int cofs = h * 128 + (lane_ & 15) * 8;
;                       v4u aa[8], cc[8];
; #pragma unroll
;                       for (int it = 0; it < 8; ++it) { const size_t row = rowbase + it * 4; aa[it] = *(const v4u*)(ORAW + row * 1024 + cofs); cc[it] = *(const v4u*)(ORAW + row * 1024 + 512 + cofs); }
; #pragma unroll
;                       for (int it = 0; it < 8; ++it) { const size_t row = rowbase + it * 4; const v4u a = aa[it], c = cc[it];
;                         float v[8] = {bf_lo(a.x) - lam * bf_lo(c.x), bf_hi(a.x) - lam * bf_hi(c.x), bf_lo(a.y) - lam * bf_lo(c.y), bf_hi(a.y) - lam * bf_hi(c.y),
;                                       bf_lo(a.z) - lam * bf_lo(c.z), bf_hi(a.z) - lam * bf_hi(c.z), bf_lo(a.w) - lam * bf_lo(c.w), bf_hi(a.w) - lam * bf_hi(c.w)};
;                         float sv = 0.f;
; #pragma unroll
;                         for (int e = 0; e < 8; ++e) sv += v[e] * v[e];
;                         sv += __shfl_xor(sv, 1); sv += __shfl_xor(sv, 2); sv += __shfl_xor(sv, 4); sv += __shfl_xor(sv, 8);
;                         const float r = __builtin_amdgcn_rsqf(sv * (1.0f / 128.0f) + EPS) * post;
;                         v4u o; o.x = pk2(v[0] * r * ga[0], v[1] * r * ga[1]); o.y = pk2(v[2] * r * ga[2], v[3] * r * ga[3]); o.z = pk2(v[4] * r * gb[0], v[5] * r * gb[1]); o.w = pk2(v[6] * r * gb[2], v[7] * r * gb[3]);
;                         *(v4u*)(MIX + row * 1024 + cofs) = o; }
.LBB0_363:
	s_setprio 0
	v_and_b32_e32 v0, 63, v206
	s_barrier
	s_load_dwordx2 s[6:7], s[62:63], 0x70
	v_lshlrev_b32_e32 v2, 3, v0
	v_and_b32_e32 v4, 0x78, v2
	v_ashrrev_i32_e32 v2, 4, v0
	v_ashrrev_i32_e32 v3, 31, v2
	s_waitcnt lgkmcnt(0)
	s_add_u32 s6, s6, s74
	s_addc_u32 s7, s7, s75
	s_add_u32 s8, s43, s67
	s_addc_u32 s9, s44, s4
	v_lshl_add_u64 v[2:3], s[8:9], 0, v[2:3]
	v_or_b32_e32 v0, s65, v4
	v_lshlrev_b64 v[54:55], 11, v[2:3]
	v_lshl_add_u64 v[2:3], s[70:71], 0, v[54:55]
	v_lshlrev_b32_e32 v0, 1, v0
	v_lshl_add_u64 v[10:11], v[2:3], 0, v[0:1]
	global_load_dwordx4 v[12:15], v[10:11], off
	global_load_dwordx4 v[58:61], v[10:11], off offset:1024
	global_load_dword v56, v1, s[72:73]
	v_and_b32_e32 v3, 64, v246
	v_xor_b32_e32 v2, 1, v246
	v_add_u32_e32 v80, 64, v3
	v_cmp_lt_i32_e32 vcc, v2, v80
	s_movk_i32 s8, 0x2000
	v_lshlrev_b32_e32 v6, 2, v4
	v_cndmask_b32_e32 v2, v246, v2, vcc
	v_add_co_u32_e32 v18, vcc, s8, v10
	v_lshlrev_b32_e32 v57, 2, v2
	global_load_dwordx4 v[2:5], v6, s[6:7] offset:16
	s_nop 0
	global_load_dwordx4 v[6:9], v6, s[6:7]
	s_mov_b64 s[6:7], 0x2000
	v_addc_co_u32_e32 v19, vcc, 0, v11, vcc
	v_lshl_add_u64 v[16:17], v[10:11], 0, s[6:7]
	global_load_dwordx4 v[62:65], v[18:19], off
	global_load_dwordx4 v[66:69], v[16:17], off offset:1024
	s_movk_i32 s9, 0x4000
	v_add_co_u32_e32 v22, vcc, s9, v10
	s_movk_i32 s12, 0x6000
	s_nop 0
	v_addc_co_u32_e32 v23, vcc, 0, v11, vcc
	v_add_co_u32_e32 v26, vcc, s12, v10
	s_mov_b32 s20, 0x8000
	s_nop 0
	v_addc_co_u32_e32 v27, vcc, 0, v11, vcc
	v_add_co_u32_e32 v30, vcc, s20, v10
	s_mov_b64 s[6:7], 0x4000
	s_nop 0
	v_addc_co_u32_e32 v31, vcc, 0, v11, vcc
	s_mov_b32 s26, 0xa000
	v_lshl_add_u64 v[20:21], v[10:11], 0, s[6:7]
	s_mov_b64 s[6:7], 0x6000
	v_add_co_u32_e32 v74, vcc, s26, v10
	v_lshl_add_u64 v[24:25], v[10:11], 0, s[6:7]
	s_mov_b64 s[6:7], 0x8000
	v_addc_co_u32_e32 v75, vcc, 0, v11, vcc
	s_mov_b32 s27, 0xc000
	v_lshl_add_u64 v[28:29], v[10:11], 0, s[6:7]
	s_mov_b64 s[6:7], 0xa000
	v_add_co_u32_e32 v16, vcc, s27, v10
	v_lshl_add_u64 v[32:33], v[10:11], 0, s[6:7]
	s_mov_b64 s[6:7], 0xc000
	v_addc_co_u32_e32 v17, vcc, 0, v11, vcc
	v_lshl_add_u64 v[76:77], v[10:11], 0, s[6:7]
	global_load_dwordx4 v[50:53], v[22:23], off
	global_load_dwordx4 v[70:73], v[20:21], off offset:1024
	global_load_dwordx4 v[42:45], v[26:27], off
	global_load_dwordx4 v[46:49], v[24:25], off offset:1024
	global_load_dwordx4 v[34:37], v[30:31], off
	global_load_dwordx4 v[38:41], v[28:29], off offset:1024
	s_nop 0
	global_load_dwordx4 v[26:29], v[74:75], off
	s_nop 0
	global_load_dwordx4 v[30:33], v[32:33], off offset:1024
	s_nop 0
	global_load_dwordx4 v[18:21], v[16:17], off
	global_load_dwordx4 v[22:25], v[76:77], off offset:1024
	s_mov_b64 s[6:7], 0xe000
	s_mov_b32 s1, 0xe000
	v_lshl_add_u64 v[78:79], v[10:11], 0, s[6:7]
	s_add_i32 s42, s42, 1
	s_movk_i32 s33, 0x2000
	s_movk_i32 s2, 0x6000
	s_cmp_eq_u32 s42, 4
	s_waitcnt vmcnt(16)
	v_lshlrev_b32_e32 v16, 16, v12
	s_waitcnt vmcnt(15)
	v_lshlrev_b32_e32 v17, 16, v58
	v_and_b32_e32 v12, 0xffff0000, v12
	v_and_b32_e32 v58, 0xffff0000, v58
	v_lshlrev_b32_e32 v74, 16, v13
	v_lshlrev_b32_e32 v75, 16, v59
	v_and_b32_e32 v13, 0xffff0000, v13
	v_and_b32_e32 v59, 0xffff0000, v59
	s_waitcnt vmcnt(14)
	v_fma_f32 v84, -v56, v58, v12
	v_fma_f32 v86, -v56, v59, v13
	v_and_b32_e32 v12, 0xffff0000, v15
	v_and_b32_e32 v13, 0xffff0000, v61
	v_lshlrev_b32_e32 v82, 16, v61
	v_fma_f32 v83, -v56, v17, v16
	v_fma_f32 v61, -v56, v13, v12
	v_mul_f32_e32 v12, v84, v84
	v_fma_f32 v85, -v56, v75, v74
	v_fmac_f32_e32 v12, v83, v83
	v_lshlrev_b32_e32 v76, 16, v14
	v_lshlrev_b32_e32 v77, 16, v60
	v_fmac_f32_e32 v12, v85, v85
	v_and_b32_e32 v14, 0xffff0000, v14
	v_and_b32_e32 v60, 0xffff0000, v60
	v_fma_f32 v76, -v56, v77, v76
	v_fmac_f32_e32 v12, v86, v86
	v_lshlrev_b32_e32 v81, 16, v15
	v_fma_f32 v77, -v56, v60, v14
	v_fmac_f32_e32 v12, v76, v76
	v_fma_f32 v81, -v56, v82, v81
	v_fmac_f32_e32 v12, v77, v77
	v_fmac_f32_e32 v12, v81, v81
	v_fmac_f32_e32 v12, v61, v61
	v_xor_b32_e32 v14, 2, v246
	v_cmp_lt_i32_e32 vcc, v14, v80
	v_lshl_add_u64 v[74:75], s[50:51], 0, v[0:1]
	s_waitcnt vmcnt(10)
	v_lshlrev_b32_e32 v82, 16, v66
	v_cndmask_b32_e32 v14, v246, v14, vcc
	v_lshlrev_b32_e32 v58, 2, v14
	s_waitcnt lgkmcnt(0)
	s_nop 1
	v_add_f32_dpp v12, v12, v12 quad_perm:[1,0,3,2] row_mask:0xf bank_mask:0xf
	v_xor_b32_e32 v14, 4, v246
	v_cmp_lt_i32_e32 vcc, v14, v80
	v_and_b32_e32 v66, 0xffff0000, v66
	v_lshl_add_u64 v[54:55], v[74:75], 0, v[54:55]
	v_cndmask_b32_e32 v14, v246, v14, vcc
	v_lshlrev_b32_e32 v59, 2, v14
	s_waitcnt lgkmcnt(0)
	s_nop 1
	v_add_f32_dpp v12, v12, v12 quad_perm:[2,3,0,1] row_mask:0xf bank_mask:0xf
	v_xor_b32_e32 v14, 8, v246
	v_cmp_lt_i32_e32 vcc, v14, v80
	s_waitcnt lgkmcnt(0)
	s_nop 1
	v_add_f32_dpp v12, v12, v12 row_half_mirror row_mask:0xf bank_mask:0xf
	v_cndmask_b32_e32 v14, v246, v14, vcc
	v_lshlrev_b32_e32 v60, 2, v14
	v_add_co_u32_e32 v10, vcc, s1, v10
	s_mov_b32 s1, 0xa000
	s_nop 0
	v_addc_co_u32_e32 v11, vcc, 0, v11, vcc
	s_waitcnt lgkmcnt(0)
; __device__ __forceinline__ float bf_lo(unsigned w) { return __uint_as_float(w << 16); }
; __device__ __forceinline__ float bf_hi(unsigned w) { return __uint_as_float(w & 0xffff0000u); }
; __device__ __forceinline__ unsigned pk2(float lo, float hi) { return pg8::cvt_pk_bf16(lo, hi); }
; __global__ void __launch_bounds__(NWAVES * 64, 2) trunk_fwd(Args args) {
;     ...
;                     { int lane_ = threadIdx.x & 63; asm volatile("" : "+v"(lane_));
;                       const float lam = LAM[li], post = 1.0f - (li == 0 ? LAMBDA_INIT0 : LAMBDA_INIT2);
;                       const f32x4* gp = (const f32x4*)(ARGIN(I_SUBLN) + li * 128 + (lane_ & 15) * 8); const f32x4 ga = gp[0], gb = gp[1];
;                       const size_t rowbase = (size_t)b * SEQ + (size_t)qb * 256 + wid * 32 + (lane_ >> 4); const int cofs = h * 128 + (lane_ & 15) * 8;
;                       v4u aa[8], cc[8];
; #pragma unroll
;                       for (int it = 0; it < 8; ++it) { const size_t row = rowbase + it * 4; aa[it] = *(const v4u*)(ORAW + row * 1024 + cofs); cc[it] = *(const v4u*)(ORAW + row * 1024 + 512 + cofs); }
; #pragma unroll
;                       for (int it = 0; it < 8; ++it) { const size_t row = rowbase + it * 4; const v4u a = aa[it], c = cc[it];
;                         float v[8] = {bf_lo(a.x) - lam * bf_lo(c.x), bf_hi(a.x) - lam * bf_hi(c.x), bf_lo(a.y) - lam * bf_lo(c.y), bf_hi(a.y) - lam * bf_hi(c.y),
;                                       bf_lo(a.z) - lam * bf_lo(c.z), bf_hi(a.z) - lam * bf_hi(c.z), bf_lo(a.w) - lam * bf_lo(c.w), bf_hi(a.w) - lam * bf_hi(c.w)};
;                         float sv = 0.f;
; #pragma unroll
;                         for (int e = 0; e < 8; ++e) sv += v[e] * v[e];
;                         sv += __shfl_xor(sv, 1); sv += __shfl_xor(sv, 2); sv += __shfl_xor(sv, 4); sv += __shfl_xor(sv, 8);
;                         const float r = __builtin_amdgcn_rsqf(sv * (1.0f / 128.0f) + EPS) * post;
;                         v4u o; o.x = pk2(v[0] * r * ga[0], v[1] * r * ga[1]); o.y = pk2(v[2] * r * ga[2], v[3] * r * ga[3]); o.z = pk2(v[4] * r * gb[0], v[5] * r * gb[1]); o.w = pk2(v[6] * r * gb[2], v[7] * r * gb[3]);
;                         *(v4u*)(MIX + row * 1024 + cofs) = o; }
	s_nop 1
	v_add_f32_dpp v12, v12, v12 row_mirror row_mask:0xf bank_mask:0xf
	v_fmamk_f32 v12, v12, 0x3c000000, v207
	v_rsq_f32_e32 v80, v12
	global_load_dwordx4 v[10:13], v[10:11], off
	s_nop 0
	global_load_dwordx4 v[14:17], v[78:79], off offset:1024
	v_mul_f32_e32 v0, v219, v80
	v_lshlrev_b32_e32 v80, 16, v62
	v_and_b32_e32 v62, 0xffff0000, v62
	v_fma_f32 v80, -v56, v82, v80
	v_fma_f32 v66, -v56, v66, v62
	v_lshlrev_b32_e32 v62, 16, v63
	v_lshlrev_b32_e32 v82, 16, v67
	v_fma_f32 v82, -v56, v82, v62
	v_and_b32_e32 v62, 0xffff0000, v63
	v_and_b32_e32 v63, 0xffff0000, v67
	v_fma_f32 v67, -v56, v63, v62
	v_lshlrev_b32_e32 v62, 16, v64
	v_lshlrev_b32_e32 v63, 16, v68
	v_mul_f32_e32 v78, v83, v0
	v_fma_f32 v83, -v56, v63, v62
	v_and_b32_e32 v62, 0xffff0000, v64
	v_and_b32_e32 v63, 0xffff0000, v68
	v_fma_f32 v68, -v56, v63, v62
	v_lshlrev_b32_e32 v62, 16, v65
	v_lshlrev_b32_e32 v63, 16, v69
	v_mul_f32_e32 v79, v84, v0
	v_fma_f32 v84, -v56, v63, v62
	v_and_b32_e32 v62, 0xffff0000, v65
	v_and_b32_e32 v63, 0xffff0000, v69
	v_fma_f32 v69, -v56, v63, v62
	v_mul_f32_e32 v63, v66, v66
	v_fmac_f32_e32 v63, v80, v80
	v_fmac_f32_e32 v63, v82, v82
	v_fmac_f32_e32 v63, v67, v67
	v_fmac_f32_e32 v63, v83, v83
	v_fmac_f32_e32 v63, v68, v68
	v_fmac_f32_e32 v63, v84, v84
	v_fmac_f32_e32 v63, v69, v69
	v_mul_f32_e32 v78, v6, v78
	v_mul_f32_e32 v62, v7, v79
	v_cvt_pk_bf16_f32 v62, v78, v62
	v_mul_f32_e32 v65, v85, v0
	s_waitcnt lgkmcnt(0)
	s_nop 1
	v_add_f32_dpp v64, v63, v63 quad_perm:[1,0,3,2] row_mask:0xf bank_mask:0xf
	v_mul_f32_e32 v63, v86, v0
	v_mul_f32_e32 v65, v8, v65
	v_mul_f32_e32 v63, v9, v63
	v_cvt_pk_bf16_f32 v63, v65, v63
	v_mul_f32_e32 v65, v76, v0
	s_waitcnt lgkmcnt(0)
	s_nop 1
	v_add_f32_dpp v76, v64, v64 quad_perm:[2,3,0,1] row_mask:0xf bank_mask:0xf
	v_mul_f32_e32 v64, v2, v65
	v_mul_f32_e32 v65, v77, v0
	v_mul_f32_e32 v65, v3, v65
	v_cvt_pk_bf16_f32 v64, v64, v65
	s_waitcnt lgkmcnt(0)
	s_nop 1
	v_add_f32_dpp v65, v76, v76 row_half_mirror row_mask:0xf bank_mask:0xf
	v_mul_f32_e32 v77, v81, v0
	v_mul_f32_e32 v0, v61, v0
	v_mul_f32_e32 v77, v4, v77
	v_mul_f32_e32 v0, v5, v0
	s_waitcnt lgkmcnt(0)
	s_nop 1
	v_add_f32_dpp v61, v65, v65 row_mirror row_mask:0xf bank_mask:0xf
	v_fmamk_f32 v61, v61, 0x3c000000, v207
	v_rsq_f32_e32 v61, v61
	v_cvt_pk_bf16_f32 v65, v77, v0
	global_store_dwordx4 v[54:55], v[62:65], off
	v_mul_f32_e32 v0, v219, v61
	s_waitcnt vmcnt(12)
	v_lshlrev_b32_e32 v63, 16, v50
	s_waitcnt vmcnt(11)
	v_lshlrev_b32_e32 v64, 16, v70
	v_fma_f32 v64, -v56, v64, v63
	v_and_b32_e32 v50, 0xffff0000, v50
	v_and_b32_e32 v63, 0xffff0000, v70
	v_fma_f32 v65, -v56, v63, v50
	v_lshlrev_b32_e32 v50, 16, v51
	v_lshlrev_b32_e32 v63, 16, v71
	v_mul_f32_e32 v62, v66, v0
	v_fma_f32 v66, -v56, v63, v50
	v_and_b32_e32 v50, 0xffff0000, v51
	v_and_b32_e32 v51, 0xffff0000, v71
	v_fma_f32 v70, -v56, v51, v50
	v_lshlrev_b32_e32 v50, 16, v52
	v_lshlrev_b32_e32 v51, 16, v72
	v_fma_f32 v71, -v56, v51, v50
	v_and_b32_e32 v50, 0xffff0000, v52
	v_and_b32_e32 v51, 0xffff0000, v72
	v_fma_f32 v72, -v56, v51, v50
	v_lshlrev_b32_e32 v50, 16, v53
	v_lshlrev_b32_e32 v51, 16, v73
	v_fma_f32 v74, -v56, v51, v50
	v_and_b32_e32 v50, 0xffff0000, v53
	v_and_b32_e32 v51, 0xffff0000, v73
	v_fma_f32 v73, -v56, v51, v50
	v_mul_f32_e32 v51, v65, v65
	v_fmac_f32_e32 v51, v64, v64
	v_fmac_f32_e32 v51, v66, v66
	v_fmac_f32_e32 v51, v70, v70
	v_fmac_f32_e32 v51, v71, v71
	v_fmac_f32_e32 v51, v72, v72
	v_fmac_f32_e32 v51, v74, v74
	v_fmac_f32_e32 v51, v73, v73
	v_mul_f32_e32 v61, v80, v0
	v_mul_f32_e32 v62, v7, v62
	v_mul_f32_e32 v61, v6, v61
	v_cvt_pk_bf16_f32 v50, v61, v62
	s_waitcnt lgkmcnt(0)
	s_nop 1
	v_add_f32_dpp v52, v51, v51 quad_perm:[1,0,3,2] row_mask:0xf bank_mask:0xf
	v_mul_f32_e32 v61, v67, v0
	v_mul_f32_e32 v51, v9, v61
	v_mul_f32_e32 v53, v82, v0
	v_mul_f32_e32 v53, v8, v53
	s_waitcnt lgkmcnt(0)
	s_nop 1
	v_add_f32_dpp v61, v52, v52 quad_perm:[2,3,0,1] row_mask:0xf bank_mask:0xf
	v_cvt_pk_bf16_f32 v51, v53, v51
	v_mul_f32_e32 v53, v83, v0
	v_mul_f32_e32 v52, v68, v0
	v_mul_f32_e32 v53, v2, v53
	s_waitcnt lgkmcnt(0)
	s_nop 1
	v_add_f32_dpp v61, v61, v61 row_half_mirror row_mask:0xf bank_mask:0xf
	v_mul_f32_e32 v52, v3, v52
	v_cvt_pk_bf16_f32 v52, v53, v52
	v_mul_f32_e32 v53, v84, v0
	v_mul_f32_e32 v0, v69, v0
	v_mul_f32_e32 v53, v4, v53
	v_mul_f32_e32 v0, v5, v0
	v_cvt_pk_bf16_f32 v53, v53, v0
	s_waitcnt lgkmcnt(0)
	s_nop 1
	v_add_f32_dpp v0, v61, v61 row_mirror row_mask:0xf bank_mask:0xf
	v_add_co_u32_e32 v62, vcc, s8, v54
	v_fmamk_f32 v0, v0, 0x3c000000, v207
	s_nop 0
	v_addc_co_u32_e32 v63, vcc, 0, v55, vcc
	global_store_dwordx4 v[62:63], v[50:53], off
	v_rsq_f32_e32 v0, v0
	s_waitcnt vmcnt(11)
	v_lshlrev_b32_e32 v52, 16, v42
	s_waitcnt vmcnt(10)
	v_lshlrev_b32_e32 v53, 16, v46
	v_and_b32_e32 v42, 0xffff0000, v42
	v_and_b32_e32 v46, 0xffff0000, v46
	v_fma_f32 v52, -v56, v53, v52
	v_fma_f32 v53, -v56, v46, v42
	v_lshlrev_b32_e32 v42, 16, v43
	v_lshlrev_b32_e32 v46, 16, v47
	v_fma_f32 v61, -v56, v46, v42
	v_and_b32_e32 v42, 0xffff0000, v43
	v_and_b32_e32 v43, 0xffff0000, v47
	v_fma_f32 v62, -v56, v43, v42
	v_lshlrev_b32_e32 v42, 16, v44
	v_lshlrev_b32_e32 v43, 16, v48
	v_fma_f32 v63, -v56, v43, v42
	v_and_b32_e32 v42, 0xffff0000, v44
	v_and_b32_e32 v43, 0xffff0000, v48
	v_mul_f32_e32 v0, v219, v0
	v_fma_f32 v48, -v56, v43, v42
	v_lshlrev_b32_e32 v42, 16, v45
	v_lshlrev_b32_e32 v43, 16, v49
	v_mul_f32_e32 v50, v64, v0
	v_fma_f32 v64, -v56, v43, v42
	v_and_b32_e32 v42, 0xffff0000, v45
	v_and_b32_e32 v43, 0xffff0000, v49
	v_fma_f32 v49, -v56, v43, v42
	v_mul_f32_e32 v43, v53, v53
	v_fmac_f32_e32 v43, v52, v52
	v_fmac_f32_e32 v43, v61, v61
	v_fmac_f32_e32 v43, v62, v62
	v_fmac_f32_e32 v43, v63, v63
	v_fmac_f32_e32 v43, v48, v48
	v_fmac_f32_e32 v43, v64, v64
	v_fmac_f32_e32 v43, v49, v49
	v_mul_f32_e32 v46, v70, v0
	v_mul_f32_e32 v45, v66, v0
	v_mul_f32_e32 v51, v65, v0
	v_mul_f32_e32 v45, v8, v45
	s_waitcnt lgkmcnt(0)
; __device__ __forceinline__ float bf_lo(unsigned w) { return __uint_as_float(w << 16); }
; __device__ __forceinline__ float bf_hi(unsigned w) { return __uint_as_float(w & 0xffff0000u); }
; __device__ __forceinline__ unsigned pk2(float lo, float hi) { return pg8::cvt_pk_bf16(lo, hi); }
; __global__ void __launch_bounds__(NWAVES * 64, 2) trunk_fwd(Args args) {
;     ...
;                     { int lane_ = threadIdx.x & 63; asm volatile("" : "+v"(lane_));
;                       const float lam = LAM[li], post = 1.0f - (li == 0 ? LAMBDA_INIT0 : LAMBDA_INIT2);
;                       const f32x4* gp = (const f32x4*)(ARGIN(I_SUBLN) + li * 128 + (lane_ & 15) * 8); const f32x4 ga = gp[0], gb = gp[1];
;                       const size_t rowbase = (size_t)b * SEQ + (size_t)qb * 256 + wid * 32 + (lane_ >> 4); const int cofs = h * 128 + (lane_ & 15) * 8;
;                       v4u aa[8], cc[8];
; #pragma unroll
;                       for (int it = 0; it < 8; ++it) { const size_t row = rowbase + it * 4; aa[it] = *(const v4u*)(ORAW + row * 1024 + cofs); cc[it] = *(const v4u*)(ORAW + row * 1024 + 512 + cofs); }
; #pragma unroll
;                       for (int it = 0; it < 8; ++it) { const size_t row = rowbase + it * 4; const v4u a = aa[it], c = cc[it];
;                         float v[8] = {bf_lo(a.x) - lam * bf_lo(c.x), bf_hi(a.x) - lam * bf_hi(c.x), bf_lo(a.y) - lam * bf_lo(c.y), bf_hi(a.y) - lam * bf_hi(c.y),
;                                       bf_lo(a.z) - lam * bf_lo(c.z), bf_hi(a.z) - lam * bf_hi(c.z), bf_lo(a.w) - lam * bf_lo(c.w), bf_hi(a.w) - lam * bf_hi(c.w)};
;                         float sv = 0.f;
; #pragma unroll
;                         for (int e = 0; e < 8; ++e) sv += v[e] * v[e];
;                         sv += __shfl_xor(sv, 1); sv += __shfl_xor(sv, 2); sv += __shfl_xor(sv, 4); sv += __shfl_xor(sv, 8);
;                         const float r = __builtin_amdgcn_rsqf(sv * (1.0f / 128.0f) + EPS) * post;
;                         v4u o; o.x = pk2(v[0] * r * ga[0], v[1] * r * ga[1]); o.y = pk2(v[2] * r * ga[2], v[3] * r * ga[3]); o.z = pk2(v[4] * r * gb[0], v[5] * r * gb[1]); o.w = pk2(v[6] * r * gb[2], v[7] * r * gb[3]);
;                         *(v4u*)(MIX + row * 1024 + cofs) = o; }
	s_nop 1
	v_add_f32_dpp v44, v43, v43 quad_perm:[1,0,3,2] row_mask:0xf bank_mask:0xf
	v_mul_f32_e32 v43, v9, v46
	v_mul_f32_e32 v50, v6, v50
	v_mul_f32_e32 v51, v7, v51
	v_cvt_pk_bf16_f32 v42, v50, v51
	s_waitcnt lgkmcnt(0)
	s_nop 1
	v_add_f32_dpp v46, v44, v44 quad_perm:[2,3,0,1] row_mask:0xf bank_mask:0xf
	v_cvt_pk_bf16_f32 v43, v45, v43
	v_mul_f32_e32 v45, v71, v0
	v_mul_f32_e32 v44, v72, v0
	v_mul_f32_e32 v45, v2, v45
	s_waitcnt lgkmcnt(0)
	s_nop 1
	v_add_f32_dpp v46, v46, v46 row_half_mirror row_mask:0xf bank_mask:0xf
	v_mul_f32_e32 v44, v3, v44
	v_cvt_pk_bf16_f32 v44, v45, v44
	v_mul_f32_e32 v45, v74, v0
	v_mul_f32_e32 v0, v73, v0
	v_mul_f32_e32 v45, v4, v45
	v_mul_f32_e32 v0, v5, v0
	v_cvt_pk_bf16_f32 v45, v45, v0
	s_waitcnt lgkmcnt(0)
	s_nop 1
	v_add_f32_dpp v0, v46, v46 row_mirror row_mask:0xf bank_mask:0xf
	v_add_co_u32_e32 v46, vcc, s9, v54
	v_fmamk_f32 v0, v0, 0x3c000000, v207
	s_nop 0
	v_addc_co_u32_e32 v47, vcc, 0, v55, vcc
	global_store_dwordx4 v[46:47], v[42:45], off
	v_rsq_f32_e32 v0, v0
	s_waitcnt vmcnt(10)
	v_lshlrev_b32_e32 v44, 16, v34
	s_waitcnt vmcnt(9)
	v_lshlrev_b32_e32 v45, 16, v38
	v_and_b32_e32 v34, 0xffff0000, v34
	v_and_b32_e32 v38, 0xffff0000, v38
	v_fma_f32 v44, -v56, v45, v44
	v_fma_f32 v45, -v56, v38, v34
	v_lshlrev_b32_e32 v34, 16, v35
	v_lshlrev_b32_e32 v38, 16, v39
	v_fma_f32 v46, -v56, v38, v34
	v_and_b32_e32 v34, 0xffff0000, v35
	v_and_b32_e32 v35, 0xffff0000, v39
	v_fma_f32 v47, -v56, v35, v34
	v_lshlrev_b32_e32 v34, 16, v36
	v_lshlrev_b32_e32 v35, 16, v40
	v_fma_f32 v50, -v56, v35, v34
	v_and_b32_e32 v34, 0xffff0000, v36
	v_and_b32_e32 v35, 0xffff0000, v40
	v_fma_f32 v40, -v56, v35, v34
	v_lshlrev_b32_e32 v34, 16, v37
	v_lshlrev_b32_e32 v35, 16, v41
	v_fma_f32 v51, -v56, v35, v34
	v_and_b32_e32 v34, 0xffff0000, v37
	v_and_b32_e32 v35, 0xffff0000, v41
	v_fma_f32 v41, -v56, v35, v34
	v_mul_f32_e32 v35, v45, v45
	v_fmac_f32_e32 v35, v44, v44
	v_fmac_f32_e32 v35, v46, v46
	v_fmac_f32_e32 v35, v47, v47
	v_fmac_f32_e32 v35, v50, v50
	v_fmac_f32_e32 v35, v40, v40
	v_fmac_f32_e32 v35, v51, v51
	v_fmac_f32_e32 v35, v41, v41
	v_mul_f32_e32 v0, v219, v0
	v_mul_f32_e32 v38, v62, v0
	v_mul_f32_e32 v37, v61, v0
	v_mul_f32_e32 v42, v52, v0
	s_waitcnt lgkmcnt(0)
	s_nop 1
	v_add_f32_dpp v36, v35, v35 quad_perm:[1,0,3,2] row_mask:0xf bank_mask:0xf
	v_mul_f32_e32 v35, v9, v38
	v_mul_f32_e32 v43, v53, v0
	v_mul_f32_e32 v37, v8, v37
	v_mul_f32_e32 v42, v6, v42
	s_waitcnt lgkmcnt(0)
	s_nop 1
	v_add_f32_dpp v38, v36, v36 quad_perm:[2,3,0,1] row_mask:0xf bank_mask:0xf
	v_mul_f32_e32 v43, v7, v43
	v_cvt_pk_bf16_f32 v34, v42, v43
	v_cvt_pk_bf16_f32 v35, v37, v35
	v_mul_f32_e32 v37, v63, v0
	s_waitcnt lgkmcnt(0)
	s_nop 1
	v_add_f32_dpp v38, v38, v38 row_half_mirror row_mask:0xf bank_mask:0xf
	v_mul_f32_e32 v36, v48, v0
	v_mul_f32_e32 v37, v2, v37
	v_mul_f32_e32 v36, v3, v36
	v_cvt_pk_bf16_f32 v36, v37, v36
	v_mul_f32_e32 v37, v64, v0
	v_mul_f32_e32 v0, v49, v0
	v_mul_f32_e32 v37, v4, v37
	v_mul_f32_e32 v0, v5, v0
	v_cvt_pk_bf16_f32 v37, v37, v0
	s_waitcnt lgkmcnt(0)
	s_nop 1
	v_add_f32_dpp v0, v38, v38 row_mirror row_mask:0xf bank_mask:0xf
	v_add_co_u32_e32 v38, vcc, s12, v54
	v_fmamk_f32 v0, v0, 0x3c000000, v207
	s_nop 0
	v_addc_co_u32_e32 v39, vcc, 0, v55, vcc
	global_store_dwordx4 v[38:39], v[34:37], off
	v_rsq_f32_e32 v0, v0
	s_waitcnt vmcnt(9)
	v_lshlrev_b32_e32 v36, 16, v26
	s_waitcnt vmcnt(8)
	v_lshlrev_b32_e32 v37, 16, v30
	v_and_b32_e32 v26, 0xffff0000, v26
	v_and_b32_e32 v30, 0xffff0000, v30
	v_fma_f32 v36, -v56, v37, v36
	v_fma_f32 v37, -v56, v30, v26
	v_lshlrev_b32_e32 v26, 16, v27
	v_lshlrev_b32_e32 v30, 16, v31
	v_fma_f32 v38, -v56, v30, v26
	v_and_b32_e32 v26, 0xffff0000, v27
	v_and_b32_e32 v27, 0xffff0000, v31
	v_fma_f32 v39, -v56, v27, v26
	v_lshlrev_b32_e32 v26, 16, v28
	v_lshlrev_b32_e32 v27, 16, v32
	v_fma_f32 v42, -v56, v27, v26
	v_and_b32_e32 v26, 0xffff0000, v28
	v_and_b32_e32 v27, 0xffff0000, v32
	v_fma_f32 v32, -v56, v27, v26
	v_lshlrev_b32_e32 v26, 16, v29
	v_lshlrev_b32_e32 v27, 16, v33
	v_fma_f32 v43, -v56, v27, v26
	v_and_b32_e32 v26, 0xffff0000, v29
	v_and_b32_e32 v27, 0xffff0000, v33
	v_fma_f32 v33, -v56, v27, v26
	v_mul_f32_e32 v27, v37, v37
	v_fmac_f32_e32 v27, v36, v36
	v_fmac_f32_e32 v27, v38, v38
	v_fmac_f32_e32 v27, v39, v39
	v_fmac_f32_e32 v27, v42, v42
	v_fmac_f32_e32 v27, v32, v32
	v_fmac_f32_e32 v27, v43, v43
	v_fmac_f32_e32 v27, v33, v33
	v_mul_f32_e32 v0, v219, v0
	v_mul_f32_e32 v30, v47, v0
	v_mul_f32_e32 v29, v46, v0
	v_mul_f32_e32 v34, v44, v0
	s_waitcnt lgkmcnt(0)
	s_nop 1
	v_add_f32_dpp v28, v27, v27 quad_perm:[1,0,3,2] row_mask:0xf bank_mask:0xf
	v_mul_f32_e32 v27, v9, v30
	v_mul_f32_e32 v35, v45, v0
	v_mul_f32_e32 v29, v8, v29
	v_mul_f32_e32 v34, v6, v34
	s_waitcnt lgkmcnt(0)
	s_nop 1
	v_add_f32_dpp v30, v28, v28 quad_perm:[2,3,0,1] row_mask:0xf bank_mask:0xf
	v_mul_f32_e32 v35, v7, v35
	v_cvt_pk_bf16_f32 v26, v34, v35
	v_cvt_pk_bf16_f32 v27, v29, v27
	v_mul_f32_e32 v29, v50, v0
	s_waitcnt lgkmcnt(0)
	s_nop 1
	v_add_f32_dpp v30, v30, v30 row_half_mirror row_mask:0xf bank_mask:0xf
	v_mul_f32_e32 v28, v40, v0
	v_mul_f32_e32 v29, v2, v29
	v_mul_f32_e32 v28, v3, v28
	v_cvt_pk_bf16_f32 v28, v29, v28
	v_mul_f32_e32 v29, v51, v0
	v_mul_f32_e32 v0, v41, v0
	v_mul_f32_e32 v29, v4, v29
	v_mul_f32_e32 v0, v5, v0
	v_cvt_pk_bf16_f32 v29, v29, v0
	s_waitcnt lgkmcnt(0)
; __device__ __forceinline__ float bf_lo(unsigned w) { return __uint_as_float(w << 16); }
; __device__ __forceinline__ float bf_hi(unsigned w) { return __uint_as_float(w & 0xffff0000u); }
; __device__ __forceinline__ unsigned pk2(float lo, float hi) { return pg8::cvt_pk_bf16(lo, hi); }
; __global__ void __launch_bounds__(NWAVES * 64, 2) trunk_fwd(Args args) {
;     ...
;                     { int lane_ = threadIdx.x & 63; asm volatile("" : "+v"(lane_));
;                       const float lam = LAM[li], post = 1.0f - (li == 0 ? LAMBDA_INIT0 : LAMBDA_INIT2);
;                       const f32x4* gp = (const f32x4*)(ARGIN(I_SUBLN) + li * 128 + (lane_ & 15) * 8); const f32x4 ga = gp[0], gb = gp[1];
;                       const size_t rowbase = (size_t)b * SEQ + (size_t)qb * 256 + wid * 32 + (lane_ >> 4); const int cofs = h * 128 + (lane_ & 15) * 8;
;                       v4u aa[8], cc[8];
; #pragma unroll
;                       for (int it = 0; it < 8; ++it) { const size_t row = rowbase + it * 4; aa[it] = *(const v4u*)(ORAW + row * 1024 + cofs); cc[it] = *(const v4u*)(ORAW + row * 1024 + 512 + cofs); }
; #pragma unroll
;                       for (int it = 0; it < 8; ++it) { const size_t row = rowbase + it * 4; const v4u a = aa[it], c = cc[it];
;                         float v[8] = {bf_lo(a.x) - lam * bf_lo(c.x), bf_hi(a.x) - lam * bf_hi(c.x), bf_lo(a.y) - lam * bf_lo(c.y), bf_hi(a.y) - lam * bf_hi(c.y),
;                                       bf_lo(a.z) - lam * bf_lo(c.z), bf_hi(a.z) - lam * bf_hi(c.z), bf_lo(a.w) - lam * bf_lo(c.w), bf_hi(a.w) - lam * bf_hi(c.w)};
;                         float sv = 0.f;
; #pragma unroll
;                         for (int e = 0; e < 8; ++e) sv += v[e] * v[e];
;                         sv += __shfl_xor(sv, 1); sv += __shfl_xor(sv, 2); sv += __shfl_xor(sv, 4); sv += __shfl_xor(sv, 8);
;                         const float r = __builtin_amdgcn_rsqf(sv * (1.0f / 128.0f) + EPS) * post;
;                         v4u o; o.x = pk2(v[0] * r * ga[0], v[1] * r * ga[1]); o.y = pk2(v[2] * r * ga[2], v[3] * r * ga[3]); o.z = pk2(v[4] * r * gb[0], v[5] * r * gb[1]); o.w = pk2(v[6] * r * gb[2], v[7] * r * gb[3]);
;                         *(v4u*)(MIX + row * 1024 + cofs) = o; }
	s_nop 1
	v_add_f32_dpp v0, v30, v30 row_mirror row_mask:0xf bank_mask:0xf
	v_add_co_u32_e32 v30, vcc, s20, v54
	v_fmamk_f32 v0, v0, 0x3c000000, v207
	s_nop 0
	v_addc_co_u32_e32 v31, vcc, 0, v55, vcc
	global_store_dwordx4 v[30:31], v[26:29], off
	v_rsq_f32_e32 v0, v0
	s_waitcnt vmcnt(8)
	v_lshlrev_b32_e32 v28, 16, v18
	s_waitcnt vmcnt(7)
	v_lshlrev_b32_e32 v29, 16, v22
	v_and_b32_e32 v18, 0xffff0000, v18
	v_and_b32_e32 v22, 0xffff0000, v22
	v_fma_f32 v28, -v56, v29, v28
	v_fma_f32 v29, -v56, v22, v18
	v_lshlrev_b32_e32 v18, 16, v19
	v_lshlrev_b32_e32 v22, 16, v23
	v_fma_f32 v30, -v56, v22, v18
	v_and_b32_e32 v18, 0xffff0000, v19
	v_and_b32_e32 v19, 0xffff0000, v23
	v_fma_f32 v31, -v56, v19, v18
	v_lshlrev_b32_e32 v18, 16, v20
	v_lshlrev_b32_e32 v19, 16, v24
	v_fma_f32 v34, -v56, v19, v18
	v_and_b32_e32 v18, 0xffff0000, v20
	v_and_b32_e32 v19, 0xffff0000, v24
	v_fma_f32 v24, -v56, v19, v18
	v_lshlrev_b32_e32 v18, 16, v21
	v_lshlrev_b32_e32 v19, 16, v25
	v_fma_f32 v35, -v56, v19, v18
	v_and_b32_e32 v18, 0xffff0000, v21
	v_and_b32_e32 v19, 0xffff0000, v25
	v_fma_f32 v25, -v56, v19, v18
	v_mul_f32_e32 v19, v29, v29
	v_fmac_f32_e32 v19, v28, v28
	v_fmac_f32_e32 v19, v30, v30
	v_fmac_f32_e32 v19, v31, v31
	v_fmac_f32_e32 v19, v34, v34
	v_fmac_f32_e32 v19, v24, v24
	v_fmac_f32_e32 v19, v35, v35
	v_fmac_f32_e32 v19, v25, v25
	v_mul_f32_e32 v0, v219, v0
	v_mul_f32_e32 v22, v39, v0
	v_mul_f32_e32 v21, v38, v0
	v_mul_f32_e32 v26, v36, v0
	s_waitcnt lgkmcnt(0)
	s_nop 1
	v_add_f32_dpp v20, v19, v19 quad_perm:[1,0,3,2] row_mask:0xf bank_mask:0xf
	v_mul_f32_e32 v19, v9, v22
	v_mul_f32_e32 v27, v37, v0
	v_mul_f32_e32 v21, v8, v21
	v_mul_f32_e32 v26, v6, v26
	s_waitcnt lgkmcnt(0)
	s_nop 1
	v_add_f32_dpp v22, v20, v20 quad_perm:[2,3,0,1] row_mask:0xf bank_mask:0xf
	v_mul_f32_e32 v27, v7, v27
	v_cvt_pk_bf16_f32 v18, v26, v27
	v_cvt_pk_bf16_f32 v19, v21, v19
	v_mul_f32_e32 v21, v42, v0
	s_waitcnt lgkmcnt(0)
	s_nop 1
	v_add_f32_dpp v22, v22, v22 row_half_mirror row_mask:0xf bank_mask:0xf
	v_mul_f32_e32 v20, v32, v0
	v_mul_f32_e32 v21, v2, v21
	v_mul_f32_e32 v20, v3, v20
	v_cvt_pk_bf16_f32 v20, v21, v20
	v_mul_f32_e32 v21, v43, v0
	v_mul_f32_e32 v0, v33, v0
	v_mul_f32_e32 v21, v4, v21
	v_mul_f32_e32 v0, v5, v0
	v_cvt_pk_bf16_f32 v21, v21, v0
	s_waitcnt lgkmcnt(0)
	s_nop 1
	v_add_f32_dpp v0, v22, v22 row_mirror row_mask:0xf bank_mask:0xf
	v_add_co_u32_e32 v22, vcc, s26, v54
	v_fmamk_f32 v0, v0, 0x3c000000, v207
	s_nop 0
	v_addc_co_u32_e32 v23, vcc, 0, v55, vcc
	global_store_dwordx4 v[22:23], v[18:21], off
	v_rsq_f32_e32 v0, v0
	s_waitcnt vmcnt(7)
	v_lshlrev_b32_e32 v20, 16, v10
	s_waitcnt vmcnt(6)
	v_lshlrev_b32_e32 v21, 16, v14
	v_and_b32_e32 v10, 0xffff0000, v10
	v_and_b32_e32 v14, 0xffff0000, v14
	v_fma_f32 v20, -v56, v21, v20
	v_fma_f32 v21, -v56, v14, v10
	v_lshlrev_b32_e32 v10, 16, v11
	v_lshlrev_b32_e32 v14, 16, v15
	v_fma_f32 v22, -v56, v14, v10
	v_and_b32_e32 v10, 0xffff0000, v11
	v_and_b32_e32 v11, 0xffff0000, v15
	v_fma_f32 v23, -v56, v11, v10
	v_lshlrev_b32_e32 v10, 16, v12
	v_lshlrev_b32_e32 v11, 16, v16
	v_fma_f32 v26, -v56, v11, v10
	v_and_b32_e32 v10, 0xffff0000, v12
	v_and_b32_e32 v11, 0xffff0000, v16
	v_fma_f32 v16, -v56, v11, v10
	v_lshlrev_b32_e32 v10, 16, v13
	v_lshlrev_b32_e32 v11, 16, v17
	v_fma_f32 v27, -v56, v11, v10
	v_and_b32_e32 v10, 0xffff0000, v13
	v_and_b32_e32 v11, 0xffff0000, v17
	v_fma_f32 v17, -v56, v11, v10
	v_mul_f32_e32 v11, v21, v21
	v_fmac_f32_e32 v11, v20, v20
	v_fmac_f32_e32 v11, v22, v22
	v_fmac_f32_e32 v11, v23, v23
	v_fmac_f32_e32 v11, v26, v26
	v_fmac_f32_e32 v11, v16, v16
	v_fmac_f32_e32 v11, v27, v27
	v_fmac_f32_e32 v11, v17, v17
	v_mul_f32_e32 v0, v219, v0
	v_mul_f32_e32 v14, v31, v0
	v_mul_f32_e32 v13, v30, v0
	v_mul_f32_e32 v18, v28, v0
	s_waitcnt lgkmcnt(0)
	s_nop 1
	v_add_f32_dpp v12, v11, v11 quad_perm:[1,0,3,2] row_mask:0xf bank_mask:0xf
	v_mul_f32_e32 v11, v9, v14
	v_mul_f32_e32 v19, v29, v0
	v_mul_f32_e32 v13, v8, v13
	v_mul_f32_e32 v18, v6, v18
	s_waitcnt lgkmcnt(0)
	s_nop 1
	v_add_f32_dpp v14, v12, v12 quad_perm:[2,3,0,1] row_mask:0xf bank_mask:0xf
	v_mul_f32_e32 v19, v7, v19
	v_cvt_pk_bf16_f32 v10, v18, v19
	v_cvt_pk_bf16_f32 v11, v13, v11
	v_mul_f32_e32 v13, v34, v0
	s_waitcnt lgkmcnt(0)
	s_nop 1
	v_add_f32_dpp v14, v14, v14 row_half_mirror row_mask:0xf bank_mask:0xf
	v_mul_f32_e32 v12, v24, v0
	v_mul_f32_e32 v13, v2, v13
	v_mul_f32_e32 v12, v3, v12
	v_cvt_pk_bf16_f32 v12, v13, v12
	v_mul_f32_e32 v13, v35, v0
	v_mul_f32_e32 v0, v25, v0
	v_mul_f32_e32 v13, v4, v13
	v_mul_f32_e32 v0, v5, v0
	v_cvt_pk_bf16_f32 v13, v13, v0
	s_waitcnt lgkmcnt(0)
	s_nop 1
	v_add_f32_dpp v0, v14, v14 row_mirror row_mask:0xf bank_mask:0xf
	v_fmamk_f32 v0, v0, 0x3c000000, v207
	v_rsq_f32_e32 v0, v0
	v_add_co_u32_e32 v14, vcc, s27, v54
	v_mul_f32_e32 v0, v219, v0
	s_nop 0
	v_addc_co_u32_e32 v15, vcc, 0, v55, vcc
	global_store_dwordx4 v[14:15], v[10:13], off
	s_nop 1
	v_mul_f32_e32 v10, v20, v0
	v_mul_f32_e32 v6, v6, v10
	v_mul_f32_e32 v10, v21, v0
	v_mul_f32_e32 v7, v7, v10
	v_cvt_pk_bf16_f32 v6, v6, v7
	v_mul_f32_e32 v7, v22, v0
	v_mul_f32_e32 v7, v8, v7
	v_mul_f32_e32 v8, v23, v0
	v_mul_f32_e32 v8, v9, v8
	v_cvt_pk_bf16_f32 v7, v7, v8
	v_mul_f32_e32 v8, v26, v0
	v_mul_f32_e32 v2, v2, v8
	v_mul_f32_e32 v8, v16, v0
	v_mul_f32_e32 v3, v3, v8
	v_cvt_pk_bf16_f32 v8, v2, v3
	v_mul_f32_e32 v2, v27, v0
	v_mul_f32_e32 v2, v4, v2
	v_mul_f32_e32 v0, v17, v0
	v_mul_f32_e32 v0, v5, v0
	v_cvt_pk_bf16_f32 v9, v2, v0
	v_add_co_u32_e32 v2, vcc, 0xe000, v54
	s_nop 1
	v_addc_co_u32_e32 v3, vcc, 0, v55, vcc
	global_store_dwordx4 v[2:3], v[6:9], off
	s_cbranch_scc1 .LBB0_357

;   #define DMA_K(t,slot) glds16(ksrc+(long)(t)*KVBLK*PQ,(unsigned)__builtin_amdgcn_readfirstlane(kdst+(slot)))
;   #define DMA_V(t,slot) glds16(vsrc+(long)(t)*KVBLK*PQ,(unsigned)__builtin_amdgcn_readfirstlane(vdst+(slot)))
; template<int THRL> __device__ __forceinline__ void attn_unit(int b,int qb,const bf16*Q,const bf16*__restrict__ K,const bf16*__restrict__ V,bf16*O,const __attribute__((address_space(3))) float*tab,char*shm){
;   int tid_=threadIdx.x; asm volatile("":"+v"(tid_)); const int tid=tid_,lane=tid&63,r32=lane&31,hi=lane>>5; const int wid=__builtin_amdgcn_readfirstlane(tid>>6);
;   const long rowbase=(long)b*SEQ; const int q0=qb*QB;
;   const bf16*Qw=Q+(rowbase+q0+wid*QBLK)*PQ;
;   const bf16*Kh=K+rowbase*PQ,*Vh=V+rowbase*PQ;
;   const unsigned lds0=(unsigned)(uintptr_t)shm;
;   float*wsf=(float*)(shm+LDS_WS)+wid*64;
;   const bf16*ksrc=Kh+(long)lane*PQ+wid*8;
;   const bf16*vsrc=Vh+(long)(16*(wid&3)+(lane>>2))*PQ+(wid>>2)*32+(lane&3)*8;
;   const unsigned kdst=lds0+LDS_K+wid*1024, vdst=lds0+LDS_V+wid*1024;
;     ...
;   const int vb0=(int)(lds0+LDS_V)+((lane>>4)&1)*32+(lane&3)*8+(4*hi+((lane&15)>>2))*64;
;   const char*Kbase=shm+LDS_K; bf16x8 kf[8];
;   const lds_cptr shm3=(lds_cptr)shm; const lds_cptr kp0=shm3+LDS_K+hi*1024+r32*16; const lds_cptr vp0=shm3+LDS_V+((lane>>4)&1)*32+(lane&3)*8+(4*hi+((lane&15)>>2))*64;
;   const int NT=(q0+QB)/KVBLK;
;   DMA_K(0,0);DMA_V(0,0);DMA_K(1,SLOTB);
;   bf16x8 qr[4];
;   #pragma unroll
;   for(int d0=0;d0<4;++d0)qr[d0]=*reinterpret_cast<const bf16x8*>(&Qw[(long)r32*PQ+d0*16+hi*8]);
.Lpf_nowait:
	v_mov_b32_e32 v34, v206
	s_and_b32 s29, s7, 64
	v_mov_b32_e32 v4, v1
	v_readfirstlane_b32 s7, v34
	s_ashr_i32 s26, s7, 6
	s_cmp_lt_u32 s26, 4
	s_cbranch_scc1 .Lprio_skip
	s_setprio 1
.Lprio_skip:
	s_lshl_b32 s88, s26, 5
	s_ashr_i32 s8, s88, 31
	s_add_u32 s82, s43, s88
	s_addc_u32 s83, s44, s8
	s_lshl_b64 s[8:9], s[82:83], 12
	s_add_u32 s8, s12, s8
	s_addc_u32 s9, s28, s9
	s_add_u32 s84, s69, s6
	v_and_b32_e32 v220, 63, v34
	s_addc_u32 s85, s49, 0
	s_lshl_b32 s28, s29, 1
	s_add_u32 s86, s55, s28
	v_lshlrev_b32_e32 v0, 12, v220
	s_addc_u32 s87, s45, 0
	s_waitcnt lgkmcnt(0)
	v_lshl_add_u64 v[2:3], s[84:85], 0, v[0:1]
	s_lshl_b32 s84, s26, 3
	s_lshl_b32 s6, s26, 4
	v_bfe_u32 v0, v34, 2, 4
	s_ashr_i32 s85, s84, 31
	v_and_or_b32 v0, s6, 48, v0
	s_ashr_i32 s6, s7, 3
	v_lshl_add_u64 v[204:205], s[84:85], 1, v[2:3]
	s_and_b32 s84, s6, 0xffffffe0
	s_ashr_i32 s85, s84, 31
	s_lshl_b32 s6, s26, 10
	v_lshlrev_b32_e32 v0, 12, v0
	v_lshlrev_b32_e32 v221, 3, v34
	s_cmp_lg_u32 0, -1
	v_lshl_add_u64 v[2:3], s[86:87], 0, v[0:1]
	v_and_b32_e32 v224, 24, v221
	s_cselect_b32 s12, 0, 0
	v_and_b32_e32 v222, 31, v34
	v_lshl_add_u64 v[2:3], s[84:85], 1, v[2:3]
	v_lshlrev_b32_e32 v0, 1, v224
	s_add_i32 s97, s6, s12
	v_bfe_u32 v223, v34, 5, 1
	v_lshl_add_u64 v[212:213], v[2:3], 0, v[0:1]
	s_add_i32 s95, s97, 0x6000
	v_lshlrev_b32_e32 v0, 12, v222
	v_lshl_add_u64 v[2:3], v[204:205], 0, s[22:23]
	s_add_i32 s12, s97, 0x2000
	v_lshl_or_b32 v0, v223, 4, v0
	s_cmp_lg_u32 s46, 0
	s_cbranch_scc1 .Lpf_pro1
	s_mov_b32 s29, m0
	s_mov_b32 m0, s97
	s_nop 0
	global_load_lds_dwordx4 v[204:205], off
	s_mov_b32 m0, s95
	s_nop 0
	global_load_lds_dwordx4 v[212:213], off
	s_mov_b32 m0, s12
	s_nop 0
	global_load_lds_dwordx4 v[2:3], off
	s_mov_b32 m0, s29
	global_load_dwordx4 v[156:159], v0, s[8:9]
	global_load_dwordx4 v[152:155], v0, s[8:9] offset:32
	global_load_dwordx4 v[148:151], v0, s[8:9] offset:64
	global_load_dwordx4 v[144:147], v0, s[8:9] offset:96
